# weight-copy items (Win and Wff1 paths): the 8 per-row gain loads issued together once per item instead of serialized pairs
# speedup vs baseline: 1.0097x; 1.0003x over previous
.LBB0_268:
	s_or_b64 exec, exec, s[0:1]
	s_cmpk_lt_u32 s5, 0x180
	s_cselect_b64 vcc, -1, 0
	v_cndmask_b32_e32 v60, 1.0, v241, vcc
	v_mov_b32_e32 v61, v60
	v_cndmask_b32_e64 v59, 0, 1, s[82:83]
	v_mov_b64_e32 v[62:63], v[60:61]
	v_cmp_ne_u32_e64 s[0:1], 1, v59
	s_andn2_b64 vcc, exec, s[82:83]
	v_mov_b32_e32 v63, v60
	s_cbranch_vccnz .LBB0_270
	s_mov_b32 s29, s35
	v_ashrrev_i32_e32 v59, 31, v58
	v_lshl_add_u64 v[62:63], s[28:29], 0, v[34:35]
	v_lshl_add_u64 v[58:59], v[58:59], 2, s[44:45]
	v_lshl_add_u64 v[62:63], v[62:63], 2, s[44:45]
	global_load_dword v80, v[58:59], off
	global_load_dword v81, v[58:59], off offset:32
	global_load_dword v82, v[58:59], off offset:64
	global_load_dword v83, v[58:59], off offset:96
	global_load_dword v84, v[58:59], off offset:128
	global_load_dword v85, v[58:59], off offset:160
	global_load_dword v86, v[58:59], off offset:192
	global_load_dword v87, v[58:59], off offset:224
	s_waitcnt vmcnt(0)
	v_mov_b32_e32 v58, v80
	v_mov_b32_e32 v59, v81
	v_pk_mul_f32 v[62:63], v[60:61], v[58:59]
.LBB0_270:
	s_waitcnt vmcnt(0)
	v_pk_mul_f32 v[12:13], v[12:13], v[62:63] op_sel_hi:[1,0]
	v_add_u32_e32 v58, v68, v69
	v_pk_mul_f32 v[14:15], v[14:15], v[62:63] op_sel_hi:[1,0]
	ds_write2_b32 v58, v12, v13 offset1:1
	ds_write2_b32 v58, v14, v15 offset0:2 offset1:3
	v_pk_mul_f32 v[0:1], v[0:1], v[62:63] op_sel:[0,1]
	v_add_u32_e32 v12, 0x420, v58
	ds_write2_b32 v12, v0, v1 offset1:1
	v_pk_mul_f32 v[0:1], v[2:3], v[62:63] op_sel:[0,1]
	v_add_u32_e32 v2, 0x428, v58
	ds_write2_b32 v2, v0, v1 offset1:1
	v_mov_b64_e32 v[0:1], v[60:61]
	s_and_b64 vcc, exec, s[0:1]
	v_mov_b32_e32 v1, v60
	s_cbranch_vccnz .LBB0_272
	s_mov_b32 s29, s35
	v_lshl_add_u64 v[0:1], s[28:29], 0, v[36:37]
	v_lshl_add_u64 v[2:3], s[28:29], 0, v[38:39]
	v_lshl_add_u64 v[0:1], v[0:1], 2, s[44:45]
	v_lshl_add_u64 v[2:3], v[2:3], 2, s[44:45]
	v_mov_b32_e32 v0, v82
	v_mov_b32_e32 v1, v83
	v_pk_mul_f32 v[0:1], v[60:61], v[0:1]
.LBB0_272:
	v_add_u32_e32 v2, v68, v70
	v_pk_mul_f32 v[14:15], v[20:21], v[0:1] op_sel_hi:[1,0]
	v_pk_mul_f32 v[4:5], v[4:5], v[0:1] op_sel:[0,1]
	v_add_u32_e32 v3, 0x420, v2
	v_pk_mul_f32 v[12:13], v[22:23], v[0:1] op_sel_hi:[1,0]
	ds_write2_b32 v2, v14, v15 offset1:1
	ds_write2_b32 v2, v12, v13 offset0:2 offset1:3
	ds_write2_b32 v3, v4, v5 offset1:1
	v_pk_mul_f32 v[0:1], v[6:7], v[0:1] op_sel:[0,1]
	v_add_u32_e32 v3, 0x428, v2
	ds_write2_b32 v3, v0, v1 offset1:1
	v_mov_b64_e32 v[0:1], v[60:61]
	s_and_b64 vcc, exec, s[0:1]
	v_mov_b32_e32 v1, v60
	s_cbranch_vccnz .LBB0_274
	s_mov_b32 s29, s35
	v_lshl_add_u64 v[0:1], s[28:29], 0, v[40:41]
	v_lshl_add_u64 v[4:5], s[28:29], 0, v[42:43]
	v_lshl_add_u64 v[0:1], v[0:1], 2, s[44:45]
	v_lshl_add_u64 v[4:5], v[4:5], 2, s[44:45]
	v_mov_b32_e32 v0, v84
	v_mov_b32_e32 v1, v85
	v_pk_mul_f32 v[0:1], v[60:61], v[0:1]
.LBB0_274:
	s_nop 0
	v_pk_mul_f32 v[6:7], v[24:25], v[0:1] op_sel_hi:[1,0]
	v_add_u32_e32 v3, 0x840, v2
	v_pk_mul_f32 v[4:5], v[26:27], v[0:1] op_sel_hi:[1,0]
	ds_write2_b32 v3, v6, v7 offset1:1
	v_add_u32_e32 v3, 0x848, v2
	ds_write2_b32 v3, v4, v5 offset1:1
	v_pk_mul_f32 v[4:5], v[8:9], v[0:1] op_sel:[0,1]
	v_add_u32_e32 v3, 0xc60, v2
	ds_write2_b32 v3, v4, v5 offset1:1
	v_pk_mul_f32 v[0:1], v[10:11], v[0:1] op_sel:[0,1]
	v_add_u32_e32 v3, 0xc68, v2
	ds_write2_b32 v3, v0, v1 offset1:1
	s_and_b64 vcc, exec, s[0:1]
	v_mov_b32_e32 v0, v60
	s_cbranch_vccnz .LBB0_276
	s_mov_b32 s29, s35
	v_lshl_add_u64 v[0:1], s[28:29], 0, v[44:45]
	v_lshl_add_u64 v[4:5], s[28:29], 0, v[46:47]
	v_lshl_add_u64 v[0:1], v[0:1], 2, s[44:45]
	v_lshl_add_u64 v[4:5], v[4:5], 2, s[44:45]
	v_mov_b32_e32 v0, v86
	v_mov_b32_e32 v1, v87
	v_pk_mul_f32 v[60:61], v[60:61], v[0:1]
	s_nop 0
	v_mov_b32_e32 v0, v61

.LBB0_301:
	s_andn2_b64 vcc, exec, s[0:1]
	s_cbranch_vccnz .LBB0_311
	s_add_i32 s0, s36, 0xfe00
	s_lshr_b32 s0, s0, 1
	s_and_b32 s5, s0, 0x7fc0
	s_and_b32 s4, s4, 0xfe0
	v_or_b32_e32 v0, s4, v67
	v_add_u32_e32 v58, s5, v32
	v_lshlrev_b32_e32 v64, 2, v0
	v_ashrrev_i32_e32 v59, 31, v58
	v_lshl_add_u64 v[0:1], s[10:11], 0, v[64:65]
	v_lshlrev_b64 v[2:3], 14, v[58:59]
	v_lshl_add_u64 v[0:1], v[0:1], 0, v[2:3]
	s_mov_b32 s0, 0x20000
	v_add_co_u32_e32 v2, vcc, s0, v0
	s_mov_b32 s0, 0x40000
	s_nop 0
	v_addc_co_u32_e32 v3, vcc, 0, v1, vcc
	global_load_dwordx4 v[28:31], v[0:1], off
	global_load_dwordx4 v[24:27], v[2:3], off
	v_add_co_u32_e32 v2, vcc, s0, v0
	s_mov_b32 s0, 0x60000
	s_nop 0
	v_addc_co_u32_e32 v3, vcc, 0, v1, vcc
	v_add_co_u32_e32 v4, vcc, s0, v0
	s_mov_b32 s0, 0x80000
	s_nop 0
	v_addc_co_u32_e32 v5, vcc, 0, v1, vcc
	global_load_dwordx4 v[20:23], v[2:3], off
	global_load_dwordx4 v[16:19], v[4:5], off
	v_add_co_u32_e32 v2, vcc, s0, v0
	v_readlane_b32 s6, v251, 58
	s_nop 0
	v_addc_co_u32_e32 v3, vcc, 0, v1, vcc
	v_add_co_u32_e32 v4, vcc, 0xa0000, v0
	v_readlane_b32 s7, v251, 59
	s_nop 0
	v_addc_co_u32_e32 v5, vcc, 0, v1, vcc
	global_load_dwordx4 v[12:15], v[2:3], off
	global_load_dwordx4 v[8:11], v[4:5], off
	v_add_co_u32_e32 v2, vcc, 0xc0000, v0
	v_cndmask_b32_e64 v61, 0, 1, s[6:7]
	s_nop 0
	v_addc_co_u32_e32 v3, vcc, 0, v1, vcc
	v_add_co_u32_e32 v0, vcc, 0xe0000, v0
	v_mov_b32_e32 v60, 1.0
	s_nop 0
	v_addc_co_u32_e32 v1, vcc, 0, v1, vcc
	global_load_dwordx4 v[4:7], v[2:3], off
	s_nop 0
	global_load_dwordx4 v[0:3], v[0:1], off
	v_cmp_ne_u32_e64 s[0:1], 1, v61
	s_andn2_b64 vcc, exec, s[6:7]
	v_lshl_add_u64 v[58:59], v[58:59], 2, s[12:13]
	v_mov_b32_e32 v62, 1.0
	s_cbranch_vccnz .LBB0_304
	global_load_dword v80, v[58:59], off
	global_load_dword v81, v[58:59], off offset:32
	global_load_dword v82, v[58:59], off offset:64
	global_load_dword v83, v[58:59], off offset:96
	global_load_dword v84, v[58:59], off offset:128
	global_load_dword v85, v[58:59], off offset:160
	global_load_dword v86, v[58:59], off offset:192
	global_load_dword v87, v[58:59], off offset:224
	s_waitcnt vmcnt(0)
	v_mov_b32_e32 v62, v80
	v_pk_mul_f32 v[28:29], v[28:29], v[62:63] op_sel_hi:[1,0]
	v_pk_mul_f32 v[30:31], v[30:31], v[62:63] op_sel_hi:[1,0]
	v_mov_b32_e32 v62, v81
.LBB0_304:
	v_add_u32_e32 v61, v68, v69
	s_waitcnt vmcnt(7)
	ds_write2_b32 v61, v28, v29 offset1:1
	ds_write2_b32 v61, v30, v31 offset0:2 offset1:3
	s_waitcnt vmcnt(0)
	v_pk_mul_f32 v[24:25], v[24:25], v[62:63] op_sel_hi:[1,0]
	v_add_u32_e32 v28, 0x420, v61
	ds_write2_b32 v28, v24, v25 offset1:1
	v_pk_mul_f32 v[24:25], v[26:27], v[62:63] op_sel_hi:[1,0]
	v_add_u32_e32 v26, 0x428, v61
	s_and_b64 vcc, exec, s[0:1]
	ds_write2_b32 v26, v24, v25 offset1:1
	s_cbranch_vccnz .LBB0_306
	v_mov_b32_e32 v24, v82
	v_mov_b32_e32 v60, v83
	v_pk_mul_f32 v[20:21], v[20:21], v[24:25] op_sel_hi:[1,0]
	v_pk_mul_f32 v[22:23], v[22:23], v[24:25] op_sel_hi:[1,0]
.LBB0_306:
	v_add_u32_e32 v24, v68, v70
	ds_write2_b32 v24, v20, v21 offset1:1
	ds_write2_b32 v24, v22, v23 offset0:2 offset1:3
	s_waitcnt vmcnt(0)
	v_pk_mul_f32 v[16:17], v[16:17], v[60:61] op_sel_hi:[1,0]
	v_add_u32_e32 v20, 0x420, v24
	ds_write2_b32 v20, v16, v17 offset1:1
	v_pk_mul_f32 v[16:17], v[18:19], v[60:61] op_sel_hi:[1,0]
	v_add_u32_e32 v18, 0x428, v24
	ds_write2_b32 v18, v16, v17 offset1:1
	v_mov_b32_e32 v16, 1.0
	s_and_b64 vcc, exec, s[0:1]
	v_mov_b32_e32 v18, 1.0
	s_cbranch_vccnz .LBB0_308
	v_mov_b32_e32 v18, v84
	v_pk_mul_f32 v[12:13], v[12:13], v[18:19] op_sel_hi:[1,0]
	v_pk_mul_f32 v[14:15], v[14:15], v[18:19] op_sel_hi:[1,0]
	v_mov_b32_e32 v18, v85
.LBB0_308:
	v_add_u32_e32 v17, 0x840, v24
	ds_write2_b32 v17, v12, v13 offset1:1
	v_add_u32_e32 v12, 0x848, v24
	ds_write2_b32 v12, v14, v15 offset1:1
	s_waitcnt vmcnt(0)
	v_pk_mul_f32 v[8:9], v[8:9], v[18:19] op_sel_hi:[1,0]
	v_add_u32_e32 v12, 0xc60, v24
	ds_write2_b32 v12, v8, v9 offset1:1
	v_pk_mul_f32 v[8:9], v[10:11], v[18:19] op_sel_hi:[1,0]
	v_add_u32_e32 v10, 0xc68, v24
	s_and_b64 vcc, exec, s[0:1]
	ds_write2_b32 v10, v8, v9 offset1:1
	s_cbranch_vccnz .LBB0_310
	v_mov_b32_e32 v8, v86
	v_mov_b32_e32 v16, v87
	v_pk_mul_f32 v[4:5], v[4:5], v[8:9] op_sel_hi:[1,0]
	v_pk_mul_f32 v[6:7], v[6:7], v[8:9] op_sel_hi:[1,0]
